# baseline (speedup 1.0000x reference)
; #define LAS __attribute__((address_space(3)))
; #define PHASE_TID() int tid_ = wv0 * 64 + ({ int l_; asm volatile("v_mbcnt_lo_u32_b32 %0, -1, 0\n\tv_mbcnt_hi_u32_b32 %0, -1, %0" : "=v"(l_)); l_; }); asm volatile("" : "+v"(tid_)); const int tid = tid_, lane = tid & 63, wave = __builtin_amdgcn_readfirstlane(tid >> 6); (void)lane; (void)wave
; __global__ void __launch_bounds__(NWAVES * 64, 2) fwd_megakernel(Params p) {
;     ...
;     grid.sync();
;     ...
;     {
;         PHASE_TID();
;         LAS float* wt = (LAS float*)lds;
;         for (int item = (G == 256 ? bid - 64 : bid); item < 64 + 256; item += (G == 256 ? 192 : G)) {
;             if (item < 0) break;
;             const bool pr = item < 64; const int n = pr ? 4096 : SKV;
;             const int bb = pr ? (item >> 3) : ((item - 64) >> 3), h = item & 7;
;             const float* cache_lf = p.in[6];
;             float v[8]; float run = 0.f;
; #pragma unroll
;             for (int i = 0; i < 8; ++i) {
;                 const int idx = tid * 8 + i; float xv = 0.f;
;                 if (idx < n) {
;                     if (pr) xv = out[O_LFP + ((size_t)bb * 4096 + idx) * 8 + h];
;                     else xv = idx < 1024 ? cache_lf[((size_t)bb * 1024 + idx) * 8 + h] : out[O_LFS + ((size_t)bb * 16 + (idx - 1024)) * 8 + h];
;                 }
;                 run += xv; v[i] = run;
;             }
;             float incl = run;
; #pragma unroll
;             for (int off = 1; off < 64; off <<= 1) { const float t2 = __shfl_up(incl, off); if (lane >= off) incl += t2; }
;             if (lane == 63) wt[wave] = incl;
;             __syncthreads();
;             float base = 0.f;
; #pragma unroll
;             for (int w = 0; w < 8; ++w) if (w < wave) base += wt[w];
;             const float excl = base + incl - run;
;             float* dst = pr ? cP + (size_t)item * 4096 : cS + (size_t)(item - 64) * SKV;
; #pragma unroll
;             for (int i = 0; i < 8; ++i) { const int idx = tid * 8 + i; if (idx < n) dst[idx] = (excl + v[i]) * att::LOG2E; }
.LBB0_30:
	v_lshrrev_b32_e32 v1, 20, v0
	v_lshrrev_b32_e32 v0, 10, v0
	v_or_b32_e32 v0, v0, v1
	s_movk_i32 s4, 0x3ff
	v_and_or_b32 v0, v0, s4, v157
	v_cmp_eq_u32_e32 vcc, 0, v0
	s_waitcnt vmcnt(0) lgkmcnt(0)
	s_barrier
	s_and_saveexec_b64 s[4:5], vcc
	s_cbranch_execz .LBB0_40
	buffer_wbl2 sc1
	s_waitcnt vmcnt(0)
	v_mov_b32_e32 v0, 0
	v_mov_b32_e32 v1, 1
	global_atomic_add v0, v1, s[92:93] offset:2048
.Lgb0_spin:
	global_load_dword v1, v0, s[92:93] offset:2048 sc1
	s_waitcnt vmcnt(0)
	v_cmp_gt_u32_e32 vcc, s94, v1
	s_cbranch_vccz .Lgb0_done
	s_sleep 2
	s_branch .Lgb0_spin
.Lgb0_done:
	buffer_inv sc1
	s_waitcnt vmcnt(0)
.LBB0_40:
	v_writelane_b32 v252, s52, 8
	s_nop 1
	v_writelane_b32 v252, s53, 9
	v_writelane_b32 v252, s54, 10
	v_writelane_b32 v252, s55, 11
	v_writelane_b32 v252, s56, 12
	v_writelane_b32 v252, s57, 13
	v_writelane_b32 v252, s58, 14
	v_writelane_b32 v252, s59, 15
	s_or_b64 exec, exec, s[4:5]
	s_add_u32 s2, s92, 0x2900000
	v_writelane_b32 v252, s2, 16
	s_addc_u32 s2, s93, 0
	v_writelane_b32 v252, s2, 17
	s_add_u32 s2, s92, 0x2a00000
	s_addc_u32 s3, s93, 0
	v_writelane_b32 v252, s2, 18
	s_sub_i32 s6, s95, 64
	s_cmpk_eq_i32 s94, 0x100
	v_writelane_b32 v252, s3, 19
	s_cselect_b64 s[4:5], -1, 0
	v_readlane_b32 s2, v252, 0
	s_barrier
	v_mbcnt_lo_u32_b32 v0, -1, 0
	v_mbcnt_hi_u32_b32 v0, -1, v0
	s_nop 0
	v_add_u32_e32 v1, s2, v0
	s_and_b64 s[2:3], s[4:5], exec
	s_cselect_b32 s33, s6, s95
	s_cmpk_gt_u32 s33, 0x13f
	v_readfirstlane_b32 s2, v1
	s_cbranch_scc1 .LBB0_121
	v_lshlrev_b32_e32 v0, 3, v1
	v_mbcnt_lo_u32_b32 v2, -1, 0
	v_mbcnt_hi_u32_b32 v51, -1, v2
	v_add_u32_e32 v2, 0xfffffc00, v0
	v_mov_b32_e32 v3, 0
	v_lshlrev_b64 v[4:5], 5, v[2:3]
	v_add_u32_e32 v2, 0xfffffc01, v0
	v_lshlrev_b64 v[10:11], 5, v[2:3]
	v_add_u32_e32 v2, 0xfffffc02, v0
	v_lshlrev_b64 v[16:17], 5, v[2:3]
	v_add_u32_e32 v2, 0xfffffc03, v0
	s_ashr_i32 s34, s2, 6
	v_lshlrev_b64 v[22:23], 5, v[2:3]
	v_add_u32_e32 v2, 0xfffffc04, v0
	s_lshl_b32 s6, s34, 2
	v_lshlrev_b64 v[28:29], 5, v[2:3]
	v_add_u32_e32 v2, 0xfffffc05, v0
	s_add_i32 s87, s6, 0
	v_lshlrev_b64 v[34:35], 5, v[2:3]
	v_add_u32_e32 v2, 0xfffffc06, v0
	s_and_b64 s[4:5], s[4:5], exec
	v_or_b32_e32 v8, 1, v0
	v_lshlrev_b64 v[40:41], 5, v[2:3]
	v_add_u32_e32 v2, 0xfffffc07, v0
	v_and_b32_e32 v52, 64, v51
	s_cselect_b32 s88, 0xc0, s94
	v_ashrrev_i32_e32 v9, 31, v8
	v_or_b32_e32 v14, 2, v0
	v_lshlrev_b64 v[46:47], 5, v[2:3]
	v_add_u32_e32 v2, -1, v51
	s_cmp_gt_i32 s34, 0
	v_lshlrev_b64 v[12:13], 5, v[8:9]
	v_ashrrev_i32_e32 v15, 31, v14
	v_or_b32_e32 v20, 3, v0
	v_cmp_lt_i32_e32 vcc, v2, v52
	v_add_u32_e32 v9, -2, v51
	s_cselect_b64 s[54:55], -1, 0
	s_cmp_gt_i32 s34, 1
	v_readlane_b32 s2, v252, 1
	v_lshlrev_b64 v[18:19], 5, v[14:15]
	v_ashrrev_i32_e32 v21, 31, v20
	v_or_b32_e32 v26, 4, v0
	v_cndmask_b32_e32 v2, v2, v51, vcc
	v_cmp_lt_i32_e32 vcc, v9, v52
	v_add_u32_e32 v15, -4, v51
	s_cselect_b64 s[56:57], -1, 0
	s_cmp_gt_i32 s34, 2
	v_readlane_b32 s3, v252, 2
	v_lshlrev_b64 v[24:25], 5, v[20:21]
	v_ashrrev_i32_e32 v27, 31, v26
	v_or_b32_e32 v32, 5, v0
	v_cndmask_b32_e32 v9, v9, v51, vcc
	v_cmp_lt_i32_e32 vcc, v15, v52
	v_add_u32_e32 v21, -8, v51
	s_cselect_b64 s[58:59], -1, 0
	s_cmp_gt_i32 s34, 3
	s_load_dwordx2 s[2:3], s[2:3], 0x30
	v_lshlrev_b64 v[30:31], 5, v[26:27]
	v_ashrrev_i32_e32 v33, 31, v32
	v_cndmask_b32_e32 v15, v15, v51, vcc
	v_cmp_lt_i32_e32 vcc, v21, v52
	v_add_u32_e32 v27, -16, v51
	s_cselect_b64 s[60:61], -1, 0
	s_cmp_gt_i32 s34, 4
	v_lshlrev_b64 v[36:37], 5, v[32:33]
	v_cndmask_b32_e32 v21, v21, v51, vcc
	v_cmp_lt_i32_e32 vcc, v27, v52
	v_subrev_u32_e32 v33, 32, v51
	s_cselect_b64 s[62:63], -1, 0
	s_cmp_gt_i32 s34, 5
	s_movk_i32 s4, 0x80
	v_or_b32_e32 v38, 6, v0
	v_or_b32_e32 v44, 7, v0
	v_cndmask_b32_e32 v27, v27, v51, vcc
	v_cmp_lt_i32_e32 vcc, v33, v52
	s_cselect_b64 s[64:65], -1, 0
	s_cmp_gt_i32 s34, 6
	v_and_b32_e32 v50, 63, v1
	v_cmp_gt_i32_e64 s[4:5], s4, v1
	v_ashrrev_i32_e32 v1, 31, v0
	s_movk_i32 s18, 0x400
	v_ashrrev_i32_e32 v39, 31, v38
	v_ashrrev_i32_e32 v45, 31, v44
	v_cndmask_b32_e32 v33, v33, v51, vcc
	s_cselect_b64 s[66:67], -1, 0
	s_cmp_gt_i32 s34, 7
	s_mov_b32 s53, 0
	v_cmp_eq_u32_e64 s[50:51], 63, v50
	v_lshlrev_b64 v[6:7], 5, v[0:1]
	v_cmp_gt_i32_e64 s[6:7], s18, v8
	v_cmp_gt_i32_e64 s[8:9], s18, v14
	v_cmp_gt_i32_e64 s[10:11], s18, v20
	v_cmp_gt_i32_e64 s[12:13], s18, v26
	v_cmp_gt_i32_e64 s[14:15], s18, v32
	v_cmp_gt_i32_e64 s[16:17], s18, v38
	v_lshlrev_b64 v[42:43], 5, v[38:39]
	v_cmp_gt_i32_e64 s[18:19], s18, v44
	v_lshlrev_b64 v[48:49], 5, v[44:45]
	v_lshlrev_b32_e32 v2, 2, v2
	v_cmp_eq_u32_e64 s[20:21], 0, v50
	v_lshlrev_b32_e32 v9, 2, v9
	v_cmp_gt_u32_e64 s[22:23], 2, v50
	v_lshlrev_b32_e32 v15, 2, v15
	v_cmp_gt_u32_e64 s[24:25], 4, v50
	v_lshlrev_b32_e32 v21, 2, v21
	v_cmp_gt_u32_e64 s[26:27], 8, v50
	v_lshlrev_b32_e32 v27, 2, v27
	v_cmp_gt_u32_e64 s[28:29], 16, v50
	v_lshlrev_b32_e32 v33, 2, v33
	v_cmp_gt_u32_e64 s[30:31], 32, v50
	s_cselect_b64 s[68:69], -1, 0
	s_lshl_b32 s89, s33, 14
	s_lshl_b32 s90, s88, 14
	s_mov_b64 s[70:71], 0x30d00000
	s_movk_i32 s91, 0x1040
	s_branch .LBB0_43
